# grid barrier: non-leader workgroups poll the top generation word directly instead of waiting for their XCD leader to republish it
# speedup vs baseline: 1.0069x; 1.0038x over previous
.LBB0_39:
	s_or_b64 exec, exec, s[20:21]
	v_cvt_f32_u32_e32 v5, v3
	s_waitcnt vmcnt(0)
	v_readfirstlane_b32 s8, v4
	v_sub_u32_e32 v4, 0, v3
	v_rcp_iflag_f32_e32 v5, v5
	v_add_u32_e32 v6, s8, v0
	v_mul_f32_e32 v5, 0x4f7ffffe, v5
	v_cvt_u32_f32_e32 v5, v5
	v_mul_lo_u32 v0, v4, v5
	v_mul_hi_u32 v0, v5, v0
	v_add_u32_e32 v0, v5, v0
	v_mul_hi_u32 v0, v6, v0
	v_mul_lo_u32 v4, v0, v3
	v_sub_u32_e32 v4, v6, v4
	v_add_u32_e32 v5, 1, v0
	v_cmp_ge_u32_e32 vcc, v4, v3
	s_nop 1
	v_cndmask_b32_e32 v0, v0, v5, vcc
	v_sub_u32_e32 v5, v4, v3
	v_cndmask_b32_e32 v4, v4, v5, vcc
	v_add_u32_e32 v5, 1, v0
	v_cmp_ge_u32_e32 vcc, v4, v3
	v_add_u32_e32 v4, 1, v6
	s_nop 0
	v_cndmask_b32_e32 v0, v0, v5, vcc
	v_mul_lo_u32 v5, v3, v0
	v_add_u32_e32 v3, v5, v3
	v_cmp_ne_u32_e32 vcc, v4, v3
	s_and_saveexec_b64 s[20:21], vcc
	s_xor_b64 s[20:21], exec, s[20:21]
	s_cbranch_execz .LBB0_53
	v_readlane_b32 s22, v254, 17
	v_readlane_b32 s23, v254, 18
	s_waitcnt lgkmcnt(0)
	s_nop 3
	global_load_dword v2, v1, s[22:23] sc1
	s_waitcnt vmcnt(0)
	v_cmp_eq_u32_e32 vcc, v2, v0
	s_and_saveexec_b64 s[22:23], vcc
	s_cbranch_execz .LBB0_52
	s_mov_b32 s8, 1
	s_mov_b64 s[24:25], 0
	s_branch .LBB0_43
